# attention QK region heads: LDS fragment reads issued in the shadows of the three opening MFMAs
# speedup vs baseline: 1.0039x; 1.0034x over previous
.LBB0_1004:
	v_mfma_f32_32x32x16_bf16 v[68:83], v[246:249], v[250:253], 0
	v_add_u32_e32 v2, s45, v189
	ds_read_b128 v[184:187], v2 offset:96
	ds_read_b128 v[210:213], v2 offset:128
	ds_read_b128 v[214:217], v2 offset:6752
	ds_read_b128 v[218:221], v2 offset:160
	ds_read_b128 v[222:225], v2 offset:6784
	v_mfma_f32_32x32x16_bf16 v[84:99], v[132:135], v[100:103], v[68:83]
	ds_read_b128 v[226:229], v2 offset:6816
	v_add_u32_e32 v2, s39, v200
	ds_read_b128 v[176:179], v2 offset:53248
	ds_read_b128 v[164:167], v2 offset:53280
	ds_read_b128 v[230:233], v2 offset:57856
	ds_read_b128 v[238:241], v2 offset:57888
	v_mfma_f32_32x32x16_bf16 v[68:83], v[136:139], v[100:103], v[68:83]
	ds_read_b128 v[160:163], v2 offset:53312
	ds_read_b128 v[156:159], v2 offset:53344
	ds_read_b128 v[242:245], v2 offset:57920
	ds_read_b128 v[152:155], v2 offset:57952
	v_exp_f32_e32 v52, v52
	v_exp_f32_e32 v183, v36
	v_exp_f32_e32 v132, v53
	v_exp_f32_e32 v53, v54
	v_mfma_f32_32x32x16_bf16 v[68:83], v[144:147], v[104:107], v[68:83]
	v_exp_f32_e32 v54, v38
	v_exp_f32_e32 v36, v55
	v_exp_f32_e32 v55, v56
	v_exp_f32_e32 v56, v40
	v_mfma_f32_32x32x16_bf16 v[84:99], v[128:131], v[104:107], v[84:99]
	v_exp_f32_e32 v40, v39
	v_exp_f32_e32 v38, v57
	v_exp_f32_e32 v57, v58
	v_exp_f32_e32 v58, v41
	v_mfma_f32_32x32x16_bf16 v[68:83], v[140:143], v[108:111], v[68:83]
	v_add_u32_e32 v181, s44, v189
	ds_read_b128 v[144:147], v181
	ds_read_b128 v[172:175], v181 offset:32
	ds_read_b128 v[136:139], v181 offset:6656
	ds_read_b128 v[168:171], v181 offset:64
	ds_read_b128 v[148:151], v181 offset:6688
	ds_read_b128 v[140:143], v181 offset:6720
	v_exp_f32_e32 v2, v37
	v_mfma_f32_32x32x16_bf16 v[84:99], v[124:127], v[108:111], v[84:99]
	v_exp_f32_e32 v124, v59
	v_exp_f32_e32 v41, v60
	v_add_f32_e32 v133, v52, v183
	v_add_f32_e32 v37, v53, v54
	s_waitcnt lgkmcnt(14)
	v_mfma_f32_32x32x16_bf16 v[68:83], v[214:217], v[112:115], v[68:83]
	v_exp_f32_e32 v214, v42
	v_exp_f32_e32 v59, v44
	v_exp_f32_e32 v60, v43
	v_exp_f32_e32 v126, v61
	v_mfma_f32_32x32x16_bf16 v[84:99], v[184:187], v[112:115], v[84:99]
	v_exp_f32_e32 v61, v62
	v_exp_f32_e32 v62, v45
	v_exp_f32_e32 v128, v63
	v_exp_f32_e32 v63, v64
	v_mfma_f32_32x32x16_bf16 v[68:83], v[222:225], v[116:119], v[68:83]
	v_exp_f32_e32 v216, v48
	v_exp_f32_e32 v64, v47
	v_exp_f32_e32 v130, v65
	v_mfma_f32_32x32x16_bf16 v[84:99], v[210:213], v[116:119], v[84:99]
	v_exp_f32_e32 v65, v66
	v_exp_f32_e32 v215, v46
	v_exp_f32_e32 v185, v50
	v_mfma_f32_32x32x16_bf16 v[68:83], v[226:229], v[120:123], v[68:83]
	v_exp_f32_e32 v66, v49
	v_exp_f32_e32 v134, v67
	v_add_f32_e32 v39, v55, v56
	v_add_f32_e32 v125, v57, v214
	v_mfma_f32_32x32x16_bf16 v[84:99], v[218:221], v[120:123], v[84:99]
	v_add_f32_e32 v127, v41, v59
	v_add_f32_e32 v129, v61, v215
	v_add_f32_e32 v131, v63, v216
	v_add_f32_e32 v135, v65, v185
	v_exp_f32_e32 v184, v51
	v_cvt_pk_bf16_f32 v42, v52, v132
	v_cvt_pk_bf16_f32 v43, v53, v36
	v_cvt_pk_bf16_f32 v44, v55, v38
	v_cvt_pk_bf16_f32 v45, v57, v124
	v_cvt_pk_bf16_f32 v46, v41, v126
	v_cvt_pk_bf16_f32 v47, v61, v128
	s_waitcnt lgkmcnt(11)
	v_mfma_f32_32x32x16_bf16 v[4:19], v[42:45], v[230:233], v[4:19]
	v_cvt_pk_bf16_f32 v48, v63, v130
	v_cvt_pk_bf16_f32 v49, v65, v134
	v_cvt_pk_bf16_f32 v50, v183, v2
	v_cvt_pk_bf16_f32 v51, v54, v40
	v_cvt_pk_bf16_f32 v52, v56, v58
	v_cvt_pk_bf16_f32 v53, v214, v60
	v_mfma_f32_32x32x16_bf16 v[20:35], v[42:45], v[176:179], v[20:35]
	v_cvt_pk_bf16_f32 v54, v59, v62
	v_cvt_pk_bf16_f32 v55, v215, v64
	v_cvt_pk_bf16_f32 v56, v216, v66
	v_cvt_pk_bf16_f32 v57, v185, v184
	s_add_i32 s14, s46, 5
	s_min_u32 s14, s14, s37
	s_add_i32 s15, s46, 3
	s_min_u32 s46, s15, s37
	s_mulk_i32 s14, 0x3000
	s_add_u32 s14, s10, s14
	s_addc_u32 s15, s11, 0
	s_lshl_b32 s46, s46, 13
	s_add_u32 s46, s12, s46
	s_addc_u32 s47, s13, 0
	s_add_i32 m0, s22, s45
	s_and_b64 s[48:49], s[4:5], exec
	s_waitcnt vmcnt(3) lgkmcnt(0)
	s_barrier
	v_mfma_f32_32x32x16_bf16 v[4:19], v[46:49], v[238:241], v[4:19]
	global_load_lds_dwordx4 v190, s[14:15]
	s_cselect_b32 s15, s15, s47
	s_cselect_b32 s14, s14, s46
	s_cselect_b32 s98, s45, s39
	s_add_i32 m0, s21, s98
	s_add_i32 s98, s23, s39
	global_load_lds_dwordx4 v192, s[14:15]
	s_add_i32 m0, s98, 0xd000
	s_nop 0
	global_load_lds_dwordx4 v194, s[46:47]
	v_max3_f32 v41, v84, v68, v85
	v_max3_f32 v59, v92, v76, v93
	v_add_f32_e32 v132, v132, v2
	v_max3_f32 v41, v41, v69, v86
	v_max3_f32 v59, v59, v77, v94
	v_mfma_f32_32x32x16_bf16 v[20:35], v[46:49], v[164:167], v[20:35]
	s_nop 0
	v_max3_f32 v41, v41, v70, v87
	v_max3_f32 v41, v41, v71, v88
	v_max3_f32 v59, v59, v78, v95
	v_max3_f32 v41, v41, v72, v89
	v_max3_f32 v59, v59, v79, v96
	s_nop 0
	v_max3_f32 v41, v41, v73, v90
	v_max3_f32 v183, v41, v74, v91
	v_mfma_f32_32x32x16_bf16 v[4:19], v[50:53], v[242:245], v[4:19]
	v_add_f32_e32 v41, v132, v133
	v_max3_f32 v59, v59, v80, v97
	v_add_f32_e64 v36, v36, v40
	v_add_f32_e64 v37, v37, v41
	v_max3_f32 v59, v59, v81, v98
	v_max3_f32 v186, v59, v82, v99
	v_add_f32_e32 v59, v36, v37
	v_add_f32_e32 v36, v38, v58
	v_add_f32_e32 v37, v39, v59
	v_mfma_f32_32x32x16_bf16 v[20:35], v[50:53], v[160:163], v[20:35]
	v_add_f32_e32 v61, v36, v37
	v_add_f32_e32 v36, v124, v60
	v_add_f32_e32 v37, v125, v61
	v_add_f32_e32 v63, v36, v37
	v_add_f32_e32 v36, v126, v62
	v_add_f32_e32 v37, v127, v63
	v_add_f32_e32 v65, v36, v37
	v_add_f32_e32 v36, v128, v64
	v_add_f32_e32 v37, v129, v65
	v_mfma_f32_32x32x16_bf16 v[20:35], v[54:57], v[156:159], v[20:35]
	v_add_f32_e32 v67, v36, v37
	v_add_f32_e32 v36, v130, v66
	v_add_f32_e32 v37, v131, v67
	v_add_f32_e32 v185, v36, v37
	v_add_f32_e32 v36, v134, v184
	v_add_f32_e32 v37, v135, v185
	v_add_f32_e32 v2, v36, v37
	v_max3_f32 v36, v183, v75, v186
	v_add_f32_e32 v2, v209, v2
	v_mfma_f32_32x32x16_bf16 v[4:19], v[54:57], v[152:155], v[4:19]
	v_max3_f32 v36, v36, v83, v36
	s_nop 0
	v_mov_b32_e32 v38, v36
	s_nop 0
	s_nop 0
	v_permlane32_swap_b32_e32 v36, v38
	v_max3_f32 v36, v36, v38, v36
	s_nop 0
	v_cmp_lt_f32_e32 vcc, s56, v36
	s_cbranch_vccz .LBB0_1008
	s_nop 0
	v_add_f32_e32 v210, v180, v36
	v_cvt_pk_bf16_f32 v210, v210, v210
	v_lshlrev_b32_e32 v210, 16, v210
	v_cndmask_b32_e32 v210, v180, v210, vcc
	v_sub_f32_e32 v36, v180, v210
	v_sub_f32_e32 v186, v210, v180
	v_xor_b32_e32 v250, 0x80000000, v210
	v_min_f32_e32 v36, 0, v36
	v_lshrrev_b32_e32 v250, 16, v250
	v_exp_f32_e32 v36, v36
	v_cndmask_b32_e64 v250, 0, v250, s[2:3]
	s_and_saveexec_b64 s[14:15], s[2:3]
	ds_write_b32 v202, v36
	s_or_b64 exec, exec, s[14:15]
	v_mul_f32_e32 v2, v2, v36
	ds_read_b32 v36, v1
	ds_read_b32 v37, v1 offset:4
	ds_read_b32 v38, v1 offset:8
	ds_read_b32 v39, v1 offset:12
	ds_read_b32 v40, v1 offset:32
	ds_read_b32 v41, v1 offset:36
	ds_read_b32 v42, v1 offset:40
	ds_read_b32 v43, v1 offset:44
	ds_read_b32 v44, v1 offset:64
	ds_read_b32 v45, v1 offset:68
	ds_read_b32 v46, v1 offset:72
	ds_read_b32 v47, v1 offset:76
	ds_read_b32 v48, v1 offset:96
	ds_read_b32 v49, v1 offset:100
	ds_read_b32 v50, v1 offset:104
	ds_read_b32 v51, v1 offset:108
	s_waitcnt lgkmcnt(0)
	v_pk_mul_f32 v[20:21], v[20:21], v[36:37]
	v_pk_mul_f32 v[22:23], v[22:23], v[38:39]
	v_pk_mul_f32 v[24:25], v[24:25], v[40:41]
	v_pk_mul_f32 v[26:27], v[26:27], v[42:43]
	v_pk_mul_f32 v[28:29], v[28:29], v[44:45]
	v_pk_mul_f32 v[30:31], v[30:31], v[46:47]
	v_pk_mul_f32 v[32:33], v[32:33], v[48:49]
	v_pk_mul_f32 v[34:35], v[34:35], v[50:51]
	v_pk_mul_f32 v[4:5], v[4:5], v[36:37]
	v_pk_mul_f32 v[6:7], v[6:7], v[38:39]
	v_pk_mul_f32 v[8:9], v[8:9], v[40:41]
	v_pk_mul_f32 v[10:11], v[10:11], v[42:43]
	v_pk_mul_f32 v[12:13], v[12:13], v[44:45]
	v_pk_mul_f32 v[14:15], v[14:15], v[46:47]
	v_pk_mul_f32 v[16:17], v[16:17], v[48:49]
	v_pk_mul_f32 v[18:19], v[18:19], v[50:51]
	v_sub_f32_e32 v68, v68, v186
	v_sub_f32_e32 v69, v69, v186
	v_sub_f32_e32 v70, v70, v186
	v_sub_f32_e32 v71, v71, v186
	v_sub_f32_e32 v72, v72, v186
	v_sub_f32_e32 v73, v73, v186
	v_sub_f32_e32 v74, v74, v186
	v_sub_f32_e32 v75, v75, v186
	v_sub_f32_e32 v76, v76, v186
	v_sub_f32_e32 v77, v77, v186
	v_sub_f32_e32 v78, v78, v186
	v_sub_f32_e32 v79, v79, v186
	v_sub_f32_e32 v80, v80, v186
	v_sub_f32_e32 v81, v81, v186
	v_sub_f32_e32 v82, v82, v186
	v_sub_f32_e32 v83, v83, v186
	v_sub_f32_e32 v84, v84, v186
	v_sub_f32_e32 v85, v85, v186
	v_sub_f32_e32 v86, v86, v186
	v_sub_f32_e32 v87, v87, v186
	v_sub_f32_e32 v88, v88, v186
	v_sub_f32_e32 v89, v89, v186
	v_sub_f32_e32 v90, v90, v186
	v_sub_f32_e32 v91, v91, v186
	v_sub_f32_e32 v92, v92, v186
	v_sub_f32_e32 v93, v93, v186
	v_sub_f32_e32 v94, v94, v186
	v_sub_f32_e32 v95, v95, v186
	v_sub_f32_e32 v96, v96, v186
	v_sub_f32_e32 v97, v97, v186
	v_sub_f32_e32 v98, v98, v186
	v_sub_f32_e32 v99, v99, v186
	s_mov_b32 s56, 0x41000000
	s_branch .LBB0_1009

.LBB0_1009:
	v_mfma_f32_32x32x16_bf16 v[36:51], v[246:249], v[250:253], 0
	v_add_u32_e32 v255, s43, v200
	ds_read_b128 v[212:215], v181 offset:96
	ds_read_b128 v[216:219], v181 offset:128
	ds_read_b128 v[220:223], v181 offset:6752
	ds_read_b128 v[224:227], v181 offset:160
	ds_read_b128 v[228:231], v181 offset:6784
	v_mfma_f32_32x32x16_bf16 v[52:67], v[144:147], v[100:103], v[36:51]
	ds_read_b128 v[238:241], v181 offset:6816
	ds_read_b128 v[160:163], v255 offset:53248
	ds_read_b128 v[164:167], v255 offset:53280
	ds_read_b128 v[184:187], v255 offset:57856
	ds_read_b128 v[180:183], v255 offset:57888
	v_mfma_f32_32x32x16_bf16 v[36:51], v[136:139], v[100:103], v[36:51]
	ds_read_b128 v[156:159], v255 offset:53312
	ds_read_b128 v[152:155], v255 offset:53344
	v_add_u32_e32 v209, s41, v189
	v_mfma_f32_32x32x16_bf16 v[36:51], v[148:151], v[104:107], v[36:51]
	ds_read_b128 v[176:179], v255 offset:57920
	ds_read_b128 v[148:151], v255 offset:57952
	v_exp_f32_e32 v211, v84
	v_exp_f32_e32 v232, v68
	v_exp_f32_e32 v233, v85
	v_exp_f32_e32 v235, v69
	v_add_f32_e32 v68, v211, v232
	v_add_f32_e32 v69, v233, v235
	v_add_f32_e32 v68, v69, v68
	v_mfma_f32_32x32x16_bf16 v[52:67], v[172:175], v[104:107], v[52:67]
	v_exp_f32_e32 v173, v70
	v_exp_f32_e32 v172, v86
	v_exp_f32_e32 v174, v87
	v_exp_f32_e32 v175, v71
	v_add_f32_e32 v69, v172, v173
	v_add_f32_e32 v68, v69, v68
	v_mfma_f32_32x32x16_bf16 v[52:67], v[168:171], v[108:111], v[52:67]
	v_add_f32_e32 v69, v174, v175
	v_add_f32_e32 v168, v69, v68
	v_exp_f32_e32 v71, v88
	v_exp_f32_e32 v85, v72
	v_exp_f32_e32 v70, v89
	v_exp_f32_e32 v84, v73
	v_exp_f32_e32 v73, v90
	v_exp_f32_e32 v87, v74
	v_exp_f32_e32 v72, v91
	v_exp_f32_e32 v86, v75
	v_add_f32_e32 v68, v70, v84
	v_add_f32_e32 v69, v71, v85
	v_mfma_f32_32x32x16_bf16 v[36:51], v[140:143], v[108:111], v[36:51]
	v_add_f32_e32 v69, v69, v168
	v_add_f32_e32 v74, v68, v69
	v_add_f32_e64 v68, v72, v86
	v_add_f32_e64 v69, v73, v87
	ds_read_b128 v[132:135], v209
	ds_read_b128 v[128:131], v209 offset:32
	ds_read_b128 v[136:139], v209 offset:6656
	ds_read_b128 v[124:127], v209 offset:64
	v_add_f32_e32 v69, v69, v74
	v_add_f32_e32 v168, v68, v69
	v_exp_f32_e32 v75, v92
	v_exp_f32_e32 v89, v76
	v_exp_f32_e32 v74, v93
	v_exp_f32_e32 v88, v77
	v_exp_f32_e32 v77, v94
	s_waitcnt lgkmcnt(12)
	v_mfma_f32_32x32x16_bf16 v[36:51], v[220:223], v[112:115], v[36:51]
	v_exp_f32_e32 v91, v78
	v_exp_f32_e32 v76, v95
	v_exp_f32_e32 v90, v79
	v_add_f32_e32 v68, v74, v88
	v_add_f32_e32 v69, v75, v89
	ds_read_b128 v[144:147], v209 offset:6688
	ds_read_b128 v[140:143], v209 offset:6720
	v_mfma_f32_32x32x16_bf16 v[52:67], v[212:215], v[112:115], v[52:67]
	v_add_f32_e32 v69, v69, v168
	v_add_f32_e32 v78, v68, v69
	v_add_f32_e64 v68, v76, v90
	v_add_f32_e64 v69, v77, v91
	v_add_f32_e32 v69, v69, v78
	v_add_f32_e32 v168, v68, v69
	v_mfma_f32_32x32x16_bf16 v[36:51], v[228:231], v[116:119], v[36:51]
	v_exp_f32_e32 v79, v96
	v_exp_f32_e32 v93, v80
	v_exp_f32_e32 v78, v97
	v_exp_f32_e32 v92, v81
	v_mfma_f32_32x32x16_bf16 v[52:67], v[216:219], v[116:119], v[52:67]
	v_exp_f32_e32 v95, v98
	v_exp_f32_e32 v97, v82
	v_exp_f32_e32 v94, v99
	v_mfma_f32_32x32x16_bf16 v[36:51], v[238:241], v[120:123], v[36:51]
	v_exp_f32_e32 v96, v83
	v_add_f32_e32 v68, v78, v92
	v_add_f32_e32 v69, v79, v93
	s_nop 0
	v_add_f32_e32 v69, v69, v168
	v_add_f32_e32 v80, v68, v69
	v_add_f32_e32 v68, v94, v96
	v_add_f32_e32 v69, v95, v97
	v_mfma_f32_32x32x16_bf16 v[52:67], v[224:227], v[120:123], v[52:67]
	v_add_f32_e32 v69, v69, v80
	v_add_f32_e32 v68, v68, v69
	v_add_f32_e32 v209, v2, v68
	v_cvt_pk_bf16_f32 v68, v211, v233
	v_cvt_pk_bf16_f32 v69, v172, v174
	v_cvt_pk_bf16_f32 v70, v71, v70
	v_cvt_pk_bf16_f32 v71, v73, v72
	v_cvt_pk_bf16_f32 v80, v75, v74
	v_cvt_pk_bf16_f32 v81, v77, v76
	s_waitcnt lgkmcnt(11)
	v_mfma_f32_32x32x16_bf16 v[4:19], v[68:71], v[184:187], v[4:19]
	v_cvt_pk_bf16_f32 v82, v79, v78
	v_cvt_pk_bf16_f32 v83, v95, v94
	v_cvt_pk_bf16_f32 v76, v232, v235
	v_cvt_pk_bf16_f32 v77, v173, v175
	v_cvt_pk_bf16_f32 v78, v85, v84
	v_cvt_pk_bf16_f32 v79, v87, v86
	v_mfma_f32_32x32x16_bf16 v[20:35], v[68:71], v[160:163], v[20:35]
	v_cvt_pk_bf16_f32 v72, v89, v88
	v_cvt_pk_bf16_f32 v73, v91, v90
	v_cvt_pk_bf16_f32 v74, v93, v92
	v_cvt_pk_bf16_f32 v75, v97, v96
	s_cmp_ge_u32 s42, s36
	s_cbranch_scc1 .Lattn_exit
	s_mov_b32 s14, s41
	s_mov_b32 s15, s38
	s_mov_b32 s41, s45
	s_mov_b32 s38, s44
	s_mov_b32 s44, s40
	s_mov_b32 s40, s43
	s_mov_b32 s46, s42
	s_add_i32 s42, s46, 4
	s_min_u32 s43, s42, s37
	s_add_i32 s42, s46, 2
	s_min_u32 s45, s42, s37
	s_mulk_i32 s43, 0x3000
	s_add_u32 s48, s10, s43
	s_addc_u32 s49, s11, 0
	s_lshl_b32 s43, s45, 13
	s_add_u32 s50, s12, s43
	s_addc_u32 s51, s13, 0
	s_add_i32 m0, s22, s38
	s_and_b64 s[52:53], s[4:5], exec
	s_waitcnt vmcnt(3) lgkmcnt(0)
	s_barrier
	s_branch .LBB0_999
